# ffn2 epilogue: 16 residual loads issued together and consumed behind counted waits, 32 stores in one run (was load/wait-all/add/store x16)
# speedup vs baseline: 1.0077x; 1.0046x over previous
;     __device__ __forceinline__ void operator()(const f32x4 (&acc)[2][2][4][2], const Unit& u, int wr, int wc, int fr, int fq) const {
;         const int col0 = u.pn * BM + wc * 32 + 8 * fq;
; #pragma unroll
;         for (int ai = 0; ai < 2; ++ai)
; #pragma unroll
;             for (int m = 0; m < 4; ++m) {
;                 const size_t off = (size_t)(u.pm * BM + ai * HALF + wr * 64 + m * 16 + fr) * 1024 + col0;
; #pragma unroll
;                 for (int bj = 0; bj < 2; ++bj) {
;                     f32x4 b0, b1; unpack8(__builtin_nontemporal_load((const u32x4*)(base + off + bj * HALF)), b0, b1);
;                     __builtin_nontemporal_store(b0 + acc[ai][bj][m][0], (f32x4*)(out + off + bj * HALF));
;                     __builtin_nontemporal_store(b1 + acc[ai][bj][m][1], (f32x4*)(out + off + bj * HALF + 4));
;                 }
;             }
;     }
.LBB0_2275:
	v_lshl_add_u32 v142, s47, 8, v144
	v_lshl_add_u32 v140, s48, 8, v146
	v_ashrrev_i32_e32 v141, 31, v140
	s_andn2_b64 vcc, exec, s[0:1]
	s_mov_b64 s[0:1], -1
	v_mov_b32_e32 v228, v142
	v_ashrrev_i32_e32 v229, 31, v228
	v_lshlrev_b64 v[228:229], 10, v[228:229]
	v_lshl_add_u64 v[228:229], v[228:229], 0, v[140:141]
	v_lshl_add_u64 v[230:231], v[228:229], 1, s[4:5]
	global_load_dwordx4 v[160:163], v[230:231], off nt
	global_load_dwordx4 v[164:167], v[230:231], off offset:256 nt
	v_or_b32_e32 v228, 16, v142
	v_ashrrev_i32_e32 v229, 31, v228
	v_lshlrev_b64 v[228:229], 10, v[228:229]
	v_lshl_add_u64 v[228:229], v[228:229], 0, v[140:141]
	v_lshl_add_u64 v[230:231], v[228:229], 1, s[4:5]
	global_load_dwordx4 v[168:171], v[230:231], off nt
	global_load_dwordx4 v[172:175], v[230:231], off offset:256 nt
	v_or_b32_e32 v228, 32, v142
	v_ashrrev_i32_e32 v229, 31, v228
	v_lshlrev_b64 v[228:229], 10, v[228:229]
	v_lshl_add_u64 v[228:229], v[228:229], 0, v[140:141]
	v_lshl_add_u64 v[230:231], v[228:229], 1, s[4:5]
	global_load_dwordx4 v[176:179], v[230:231], off nt
	global_load_dwordx4 v[180:183], v[230:231], off offset:256 nt
	v_or_b32_e32 v228, 48, v142
	v_ashrrev_i32_e32 v229, 31, v228
	v_lshlrev_b64 v[228:229], 10, v[228:229]
	v_lshl_add_u64 v[228:229], v[228:229], 0, v[140:141]
	v_lshl_add_u64 v[230:231], v[228:229], 1, s[4:5]
	global_load_dwordx4 v[184:187], v[230:231], off nt
	global_load_dwordx4 v[188:191], v[230:231], off offset:256 nt
	v_add_u32_e32 v228, 0x80, v142
	v_ashrrev_i32_e32 v229, 31, v228
	v_lshlrev_b64 v[228:229], 10, v[228:229]
	v_lshl_add_u64 v[228:229], v[228:229], 0, v[140:141]
	v_lshl_add_u64 v[230:231], v[228:229], 1, s[4:5]
	global_load_dwordx4 v[192:195], v[230:231], off nt
	global_load_dwordx4 v[196:199], v[230:231], off offset:256 nt
	v_add_u32_e32 v228, 0x90, v142
	v_ashrrev_i32_e32 v229, 31, v228
	v_lshlrev_b64 v[228:229], 10, v[228:229]
	v_lshl_add_u64 v[228:229], v[228:229], 0, v[140:141]
	v_lshl_add_u64 v[230:231], v[228:229], 1, s[4:5]
	global_load_dwordx4 v[200:203], v[230:231], off nt
	global_load_dwordx4 v[204:207], v[230:231], off offset:256 nt
	v_add_u32_e32 v228, 0xa0, v142
	v_ashrrev_i32_e32 v229, 31, v228
	v_lshlrev_b64 v[228:229], 10, v[228:229]
	v_lshl_add_u64 v[228:229], v[228:229], 0, v[140:141]
	v_lshl_add_u64 v[230:231], v[228:229], 1, s[4:5]
	global_load_dwordx4 v[208:211], v[230:231], off nt
	global_load_dwordx4 v[212:215], v[230:231], off offset:256 nt
	v_add_u32_e32 v228, 0xb0, v142
	v_ashrrev_i32_e32 v229, 31, v228
	v_lshlrev_b64 v[228:229], 10, v[228:229]
	v_lshl_add_u64 v[228:229], v[228:229], 0, v[140:141]
	v_lshl_add_u64 v[230:231], v[228:229], 1, s[4:5]
	global_load_dwordx4 v[216:219], v[230:231], off nt
	global_load_dwordx4 v[220:223], v[230:231], off offset:256 nt
	s_waitcnt vmcnt(15)
	v_lshlrev_b32_e32 v232, 16, v160
	v_and_b32_e32 v233, 0xffff0000, v160
	v_lshlrev_b32_e32 v234, 16, v161
	v_and_b32_e32 v235, 0xffff0000, v161
	v_lshlrev_b32_e32 v236, 16, v162
	v_and_b32_e32 v237, 0xffff0000, v162
	v_lshlrev_b32_e32 v238, 16, v163
	v_and_b32_e32 v239, 0xffff0000, v163
	v_pk_add_f32 v[124:125], v[124:125], v[232:233]
	v_pk_add_f32 v[126:127], v[126:127], v[234:235]
	v_pk_add_f32 v[120:121], v[120:121], v[236:237]
	v_pk_add_f32 v[122:123], v[122:123], v[238:239]
	s_waitcnt vmcnt(14)
	v_lshlrev_b32_e32 v232, 16, v164
	v_and_b32_e32 v233, 0xffff0000, v164
	v_lshlrev_b32_e32 v234, 16, v165
	v_and_b32_e32 v235, 0xffff0000, v165
	v_lshlrev_b32_e32 v236, 16, v166
	v_and_b32_e32 v237, 0xffff0000, v166
	v_lshlrev_b32_e32 v238, 16, v167
	v_and_b32_e32 v239, 0xffff0000, v167
	v_pk_add_f32 v[116:117], v[116:117], v[232:233]
	v_pk_add_f32 v[118:119], v[118:119], v[234:235]
	v_pk_add_f32 v[112:113], v[112:113], v[236:237]
	v_pk_add_f32 v[114:115], v[114:115], v[238:239]
	s_waitcnt vmcnt(13)
	v_lshlrev_b32_e32 v232, 16, v168
	v_and_b32_e32 v233, 0xffff0000, v168
	v_lshlrev_b32_e32 v234, 16, v169
	v_and_b32_e32 v235, 0xffff0000, v169
	v_lshlrev_b32_e32 v236, 16, v170
	v_and_b32_e32 v237, 0xffff0000, v170
	v_lshlrev_b32_e32 v238, 16, v171
	v_and_b32_e32 v239, 0xffff0000, v171
	v_pk_add_f32 v[108:109], v[108:109], v[232:233]
	v_pk_add_f32 v[110:111], v[110:111], v[234:235]
	v_pk_add_f32 v[104:105], v[104:105], v[236:237]
	v_pk_add_f32 v[106:107], v[106:107], v[238:239]
	s_waitcnt vmcnt(12)
	v_lshlrev_b32_e32 v232, 16, v172
	v_and_b32_e32 v233, 0xffff0000, v172
	v_lshlrev_b32_e32 v234, 16, v173
	v_and_b32_e32 v235, 0xffff0000, v173
	v_lshlrev_b32_e32 v236, 16, v174
	v_and_b32_e32 v237, 0xffff0000, v174
	v_lshlrev_b32_e32 v238, 16, v175
	v_and_b32_e32 v239, 0xffff0000, v175
	v_pk_add_f32 v[100:101], v[100:101], v[232:233]
	v_pk_add_f32 v[102:103], v[102:103], v[234:235]
	v_pk_add_f32 v[96:97], v[96:97], v[236:237]
	v_pk_add_f32 v[98:99], v[98:99], v[238:239]
	s_waitcnt vmcnt(11)
	v_lshlrev_b32_e32 v232, 16, v176
	v_and_b32_e32 v233, 0xffff0000, v176
	v_lshlrev_b32_e32 v234, 16, v177
	v_and_b32_e32 v235, 0xffff0000, v177
	v_lshlrev_b32_e32 v236, 16, v178
	v_and_b32_e32 v237, 0xffff0000, v178
	v_lshlrev_b32_e32 v238, 16, v179
	v_and_b32_e32 v239, 0xffff0000, v179
	v_pk_add_f32 v[92:93], v[92:93], v[232:233]
	v_pk_add_f32 v[94:95], v[94:95], v[234:235]
	v_pk_add_f32 v[88:89], v[88:89], v[236:237]
	v_pk_add_f32 v[90:91], v[90:91], v[238:239]
	s_waitcnt vmcnt(10)
	v_lshlrev_b32_e32 v232, 16, v180
	v_and_b32_e32 v233, 0xffff0000, v180
	v_lshlrev_b32_e32 v234, 16, v181
	v_and_b32_e32 v235, 0xffff0000, v181
	v_lshlrev_b32_e32 v236, 16, v182
	v_and_b32_e32 v237, 0xffff0000, v182
	v_lshlrev_b32_e32 v238, 16, v183
	v_and_b32_e32 v239, 0xffff0000, v183
	v_pk_add_f32 v[84:85], v[84:85], v[232:233]
	v_pk_add_f32 v[86:87], v[86:87], v[234:235]
	v_pk_add_f32 v[80:81], v[80:81], v[236:237]
	v_pk_add_f32 v[82:83], v[82:83], v[238:239]
	s_waitcnt vmcnt(9)
;     __device__ __forceinline__ void operator()(const f32x4 (&acc)[2][2][4][2], const Unit& u, int wr, int wc, int fr, int fq) const {
;         const int col0 = u.pn * BM + wc * 32 + 8 * fq;
; #pragma unroll
;         for (int ai = 0; ai < 2; ++ai)
; #pragma unroll
;             for (int m = 0; m < 4; ++m) {
;                 const size_t off = (size_t)(u.pm * BM + ai * HALF + wr * 64 + m * 16 + fr) * 1024 + col0;
; #pragma unroll
;                 for (int bj = 0; bj < 2; ++bj) {
;                     f32x4 b0, b1; unpack8(__builtin_nontemporal_load((const u32x4*)(base + off + bj * HALF)), b0, b1);
;                     __builtin_nontemporal_store(b0 + acc[ai][bj][m][0], (f32x4*)(out + off + bj * HALF));
;                     __builtin_nontemporal_store(b1 + acc[ai][bj][m][1], (f32x4*)(out + off + bj * HALF + 4));
;                 }
;             }
;     }
	v_lshlrev_b32_e32 v232, 16, v184
	v_and_b32_e32 v233, 0xffff0000, v184
	v_lshlrev_b32_e32 v234, 16, v185
	v_and_b32_e32 v235, 0xffff0000, v185
	v_lshlrev_b32_e32 v236, 16, v186
	v_and_b32_e32 v237, 0xffff0000, v186
	v_lshlrev_b32_e32 v238, 16, v187
	v_and_b32_e32 v239, 0xffff0000, v187
	v_pk_add_f32 v[76:77], v[76:77], v[232:233]
	v_pk_add_f32 v[78:79], v[78:79], v[234:235]
	v_pk_add_f32 v[72:73], v[72:73], v[236:237]
	v_pk_add_f32 v[74:75], v[74:75], v[238:239]
	s_waitcnt vmcnt(8)
	v_lshlrev_b32_e32 v232, 16, v188
	v_and_b32_e32 v233, 0xffff0000, v188
	v_lshlrev_b32_e32 v234, 16, v189
	v_and_b32_e32 v235, 0xffff0000, v189
	v_lshlrev_b32_e32 v236, 16, v190
	v_and_b32_e32 v237, 0xffff0000, v190
	v_lshlrev_b32_e32 v238, 16, v191
	v_and_b32_e32 v239, 0xffff0000, v191
	v_pk_add_f32 v[68:69], v[68:69], v[232:233]
	v_pk_add_f32 v[70:71], v[70:71], v[234:235]
	v_pk_add_f32 v[64:65], v[64:65], v[236:237]
	v_pk_add_f32 v[66:67], v[66:67], v[238:239]
	s_waitcnt vmcnt(7)
	v_lshlrev_b32_e32 v232, 16, v192
	v_and_b32_e32 v233, 0xffff0000, v192
	v_lshlrev_b32_e32 v234, 16, v193
	v_and_b32_e32 v235, 0xffff0000, v193
	v_lshlrev_b32_e32 v236, 16, v194
	v_and_b32_e32 v237, 0xffff0000, v194
	v_lshlrev_b32_e32 v238, 16, v195
	v_and_b32_e32 v239, 0xffff0000, v195
	v_pk_add_f32 v[60:61], v[60:61], v[232:233]
	v_pk_add_f32 v[62:63], v[62:63], v[234:235]
	v_pk_add_f32 v[56:57], v[56:57], v[236:237]
	v_pk_add_f32 v[58:59], v[58:59], v[238:239]
	s_waitcnt vmcnt(6)
	v_lshlrev_b32_e32 v232, 16, v196
	v_and_b32_e32 v233, 0xffff0000, v196
	v_lshlrev_b32_e32 v234, 16, v197
	v_and_b32_e32 v235, 0xffff0000, v197
	v_lshlrev_b32_e32 v236, 16, v198
	v_and_b32_e32 v237, 0xffff0000, v198
	v_lshlrev_b32_e32 v238, 16, v199
	v_and_b32_e32 v239, 0xffff0000, v199
	v_pk_add_f32 v[52:53], v[52:53], v[232:233]
	v_pk_add_f32 v[54:55], v[54:55], v[234:235]
	v_pk_add_f32 v[48:49], v[48:49], v[236:237]
	v_pk_add_f32 v[50:51], v[50:51], v[238:239]
	s_waitcnt vmcnt(5)
	v_lshlrev_b32_e32 v232, 16, v200
	v_and_b32_e32 v233, 0xffff0000, v200
	v_lshlrev_b32_e32 v234, 16, v201
	v_and_b32_e32 v235, 0xffff0000, v201
	v_lshlrev_b32_e32 v236, 16, v202
	v_and_b32_e32 v237, 0xffff0000, v202
	v_lshlrev_b32_e32 v238, 16, v203
	v_and_b32_e32 v239, 0xffff0000, v203
	v_pk_add_f32 v[44:45], v[44:45], v[232:233]
	v_pk_add_f32 v[46:47], v[46:47], v[234:235]
	v_pk_add_f32 v[40:41], v[40:41], v[236:237]
	v_pk_add_f32 v[42:43], v[42:43], v[238:239]
	s_waitcnt vmcnt(4)
	v_lshlrev_b32_e32 v232, 16, v204
	v_and_b32_e32 v233, 0xffff0000, v204
	v_lshlrev_b32_e32 v234, 16, v205
	v_and_b32_e32 v235, 0xffff0000, v205
	v_lshlrev_b32_e32 v236, 16, v206
	v_and_b32_e32 v237, 0xffff0000, v206
	v_lshlrev_b32_e32 v238, 16, v207
	v_and_b32_e32 v239, 0xffff0000, v207
	v_pk_add_f32 v[36:37], v[36:37], v[232:233]
	v_pk_add_f32 v[38:39], v[38:39], v[234:235]
	v_pk_add_f32 v[32:33], v[32:33], v[236:237]
	v_pk_add_f32 v[34:35], v[34:35], v[238:239]
	s_waitcnt vmcnt(3)
	v_lshlrev_b32_e32 v232, 16, v208
	v_and_b32_e32 v233, 0xffff0000, v208
	v_lshlrev_b32_e32 v234, 16, v209
	v_and_b32_e32 v235, 0xffff0000, v209
	v_lshlrev_b32_e32 v236, 16, v210
	v_and_b32_e32 v237, 0xffff0000, v210
	v_lshlrev_b32_e32 v238, 16, v211
	v_and_b32_e32 v239, 0xffff0000, v211
	v_pk_add_f32 v[28:29], v[28:29], v[232:233]
	v_pk_add_f32 v[30:31], v[30:31], v[234:235]
	v_pk_add_f32 v[24:25], v[24:25], v[236:237]
	v_pk_add_f32 v[26:27], v[26:27], v[238:239]
	s_waitcnt vmcnt(2)
	v_lshlrev_b32_e32 v232, 16, v212
	v_and_b32_e32 v233, 0xffff0000, v212
	v_lshlrev_b32_e32 v234, 16, v213
	v_and_b32_e32 v235, 0xffff0000, v213
	v_lshlrev_b32_e32 v236, 16, v214
	v_and_b32_e32 v237, 0xffff0000, v214
	v_lshlrev_b32_e32 v238, 16, v215
	v_and_b32_e32 v239, 0xffff0000, v215
	v_pk_add_f32 v[20:21], v[20:21], v[232:233]
	v_pk_add_f32 v[22:23], v[22:23], v[234:235]
	v_pk_add_f32 v[16:17], v[16:17], v[236:237]
	v_pk_add_f32 v[18:19], v[18:19], v[238:239]
	s_waitcnt vmcnt(1)
	v_lshlrev_b32_e32 v232, 16, v216
	v_and_b32_e32 v233, 0xffff0000, v216
	v_lshlrev_b32_e32 v234, 16, v217
	v_and_b32_e32 v235, 0xffff0000, v217
	v_lshlrev_b32_e32 v236, 16, v218
	v_and_b32_e32 v237, 0xffff0000, v218
	v_lshlrev_b32_e32 v238, 16, v219
	v_and_b32_e32 v239, 0xffff0000, v219
	v_pk_add_f32 v[12:13], v[12:13], v[232:233]
	v_pk_add_f32 v[14:15], v[14:15], v[234:235]
	v_pk_add_f32 v[8:9], v[8:9], v[236:237]
	v_pk_add_f32 v[10:11], v[10:11], v[238:239]
	s_waitcnt vmcnt(0)
;     __device__ __forceinline__ void operator()(const f32x4 (&acc)[2][2][4][2], const Unit& u, int wr, int wc, int fr, int fq) const {
;         const int col0 = u.pn * BM + wc * 32 + 8 * fq;
; #pragma unroll
;         for (int ai = 0; ai < 2; ++ai)
; #pragma unroll
;             for (int m = 0; m < 4; ++m) {
;                 const size_t off = (size_t)(u.pm * BM + ai * HALF + wr * 64 + m * 16 + fr) * 1024 + col0;
; #pragma unroll
;                 for (int bj = 0; bj < 2; ++bj) {
;                     f32x4 b0, b1; unpack8(__builtin_nontemporal_load((const u32x4*)(base + off + bj * HALF)), b0, b1);
;                     __builtin_nontemporal_store(b0 + acc[ai][bj][m][0], (f32x4*)(out + off + bj * HALF));
;                     __builtin_nontemporal_store(b1 + acc[ai][bj][m][1], (f32x4*)(out + off + bj * HALF + 4));
;                 }
;             }
;     }
	v_lshlrev_b32_e32 v232, 16, v220
	v_and_b32_e32 v233, 0xffff0000, v220
	v_lshlrev_b32_e32 v234, 16, v221
	v_and_b32_e32 v235, 0xffff0000, v221
	v_lshlrev_b32_e32 v236, 16, v222
	v_and_b32_e32 v237, 0xffff0000, v222
	v_lshlrev_b32_e32 v238, 16, v223
	v_and_b32_e32 v239, 0xffff0000, v223
	v_pk_add_f32 v[4:5], v[4:5], v[232:233]
	v_pk_add_f32 v[6:7], v[6:7], v[234:235]
	v_pk_add_f32 v[0:1], v[0:1], v[236:237]
	v_pk_add_f32 v[2:3], v[2:3], v[238:239]
	v_mov_b32_e32 v228, v142
	v_ashrrev_i32_e32 v229, 31, v228
	v_lshlrev_b64 v[228:229], 10, v[228:229]
	v_lshl_add_u64 v[228:229], v[228:229], 0, v[140:141]
	v_lshl_add_u64 v[230:231], v[228:229], 2, s[40:41]
	global_store_dwordx4 v[230:231], v[124:127], off nt
	global_store_dwordx4 v[230:231], v[120:123], off offset:16 nt
	global_store_dwordx4 v[230:231], v[116:119], off offset:512 nt
	global_store_dwordx4 v[230:231], v[112:115], off offset:528 nt
	v_or_b32_e32 v228, 16, v142
	v_ashrrev_i32_e32 v229, 31, v228
	v_lshlrev_b64 v[228:229], 10, v[228:229]
	v_lshl_add_u64 v[228:229], v[228:229], 0, v[140:141]
	v_lshl_add_u64 v[230:231], v[228:229], 2, s[40:41]
	global_store_dwordx4 v[230:231], v[108:111], off nt
	global_store_dwordx4 v[230:231], v[104:107], off offset:16 nt
	global_store_dwordx4 v[230:231], v[100:103], off offset:512 nt
	global_store_dwordx4 v[230:231], v[96:99], off offset:528 nt
	v_or_b32_e32 v228, 32, v142
	v_ashrrev_i32_e32 v229, 31, v228
	v_lshlrev_b64 v[228:229], 10, v[228:229]
	v_lshl_add_u64 v[228:229], v[228:229], 0, v[140:141]
	v_lshl_add_u64 v[230:231], v[228:229], 2, s[40:41]
	global_store_dwordx4 v[230:231], v[92:95], off nt
	global_store_dwordx4 v[230:231], v[88:91], off offset:16 nt
	global_store_dwordx4 v[230:231], v[84:87], off offset:512 nt
	global_store_dwordx4 v[230:231], v[80:83], off offset:528 nt
	v_or_b32_e32 v228, 48, v142
	v_ashrrev_i32_e32 v229, 31, v228
	v_lshlrev_b64 v[228:229], 10, v[228:229]
	v_lshl_add_u64 v[228:229], v[228:229], 0, v[140:141]
	v_lshl_add_u64 v[230:231], v[228:229], 2, s[40:41]
	global_store_dwordx4 v[230:231], v[76:79], off nt
	global_store_dwordx4 v[230:231], v[72:75], off offset:16 nt
	global_store_dwordx4 v[230:231], v[68:71], off offset:512 nt
	global_store_dwordx4 v[230:231], v[64:67], off offset:528 nt
	v_add_u32_e32 v228, 0x80, v142
	v_ashrrev_i32_e32 v229, 31, v228
	v_lshlrev_b64 v[228:229], 10, v[228:229]
	v_lshl_add_u64 v[228:229], v[228:229], 0, v[140:141]
	v_lshl_add_u64 v[230:231], v[228:229], 2, s[40:41]
	global_store_dwordx4 v[230:231], v[60:63], off nt
	global_store_dwordx4 v[230:231], v[56:59], off offset:16 nt
	global_store_dwordx4 v[230:231], v[52:55], off offset:512 nt
	global_store_dwordx4 v[230:231], v[48:51], off offset:528 nt
	v_add_u32_e32 v228, 0x90, v142
	v_ashrrev_i32_e32 v229, 31, v228
	v_lshlrev_b64 v[228:229], 10, v[228:229]
	v_lshl_add_u64 v[228:229], v[228:229], 0, v[140:141]
	v_lshl_add_u64 v[230:231], v[228:229], 2, s[40:41]
	global_store_dwordx4 v[230:231], v[44:47], off nt
	global_store_dwordx4 v[230:231], v[40:43], off offset:16 nt
	global_store_dwordx4 v[230:231], v[36:39], off offset:512 nt
	global_store_dwordx4 v[230:231], v[32:35], off offset:528 nt
	v_add_u32_e32 v228, 0xa0, v142
	v_ashrrev_i32_e32 v229, 31, v228
	v_lshlrev_b64 v[228:229], 10, v[228:229]
	v_lshl_add_u64 v[228:229], v[228:229], 0, v[140:141]
	v_lshl_add_u64 v[230:231], v[228:229], 2, s[40:41]
	global_store_dwordx4 v[230:231], v[28:31], off nt
	global_store_dwordx4 v[230:231], v[24:27], off offset:16 nt
	global_store_dwordx4 v[230:231], v[20:23], off offset:512 nt
	global_store_dwordx4 v[230:231], v[16:19], off offset:528 nt
	v_add_u32_e32 v228, 0xb0, v142
	v_ashrrev_i32_e32 v229, 31, v228
	v_lshlrev_b64 v[228:229], 10, v[228:229]
	v_lshl_add_u64 v[228:229], v[228:229], 0, v[140:141]
	v_lshl_add_u64 v[230:231], v[228:229], 2, s[40:41]
	global_store_dwordx4 v[230:231], v[12:15], off nt
	global_store_dwordx4 v[230:231], v[8:11], off offset:16 nt
	global_store_dwordx4 v[230:231], v[4:7], off offset:512 nt
	global_store_dwordx4 v[230:231], v[0:3], off offset:528 nt
	s_cbranch_vccnz .LBB0_2264
	s_andn2_b64 vcc, exec, s[2:3]
	s_cbranch_vccnz .LBB0_2263
	s_barrier
	s_branch .LBB0_2263
